# phase 1: one dword-per-lane L2 warm-up load two rows ahead (new lever: software cache prefetch for a latency-bound streaming loop)
# baseline (speedup 1.0000x reference)
.LBB0_233:
	s_or_b64 exec, exec, s[16:17]
	v_mul_f32_e32 v88, v29, v29
	v_fmac_f32_e32 v88, v28, v28
	v_fmac_f32_e32 v88, v30, v30
	v_fmac_f32_e32 v88, v31, v31
	v_fmac_f32_e32 v88, v24, v24
	v_fmac_f32_e32 v88, v25, v25
	v_fmac_f32_e32 v88, v26, v26
	v_fmac_f32_e32 v88, v27, v27
	v_fmac_f32_e32 v88, v20, v20
	v_fmac_f32_e32 v88, v21, v21
	v_fmac_f32_e32 v88, v22, v22
	v_fmac_f32_e32 v88, v23, v23
	v_pk_mul_f32 v[100:101], v[16:17], v[16:17]
	v_pk_mul_f32 v[98:99], v[18:19], v[18:19]
	v_add_f32_e32 v88, v100, v88
	v_add_f32_e32 v88, v101, v88
	v_add_f32_e32 v88, v98, v88
	v_add_f32_e32 v88, v99, v88
	ds_bpermute_b32 v98, v89, v88
	s_and_b64 s[2:3], exec, s[2:3]
	s_or_b64 s[8:9], s[2:3], s[8:9]
	v_lshl_add_u64 v[66:67], v[66:67], 0, s[6:7]
	s_waitcnt lgkmcnt(0)
	v_add_f32_e32 v88, v88, v98
	ds_bpermute_b32 v98, v92, v88
	s_waitcnt lgkmcnt(0)
	v_add_f32_e32 v88, v88, v98
	ds_bpermute_b32 v98, v93, v88
	s_waitcnt lgkmcnt(0)
	v_add_f32_e32 v88, v88, v98
	ds_bpermute_b32 v98, v94, v88
	s_waitcnt lgkmcnt(0)
	v_add_f32_e32 v88, v88, v98
	ds_bpermute_b32 v98, v95, v88
	s_waitcnt lgkmcnt(0)
	v_add_f32_e32 v88, v88, v98
	ds_bpermute_b32 v98, v96, v88
	s_waitcnt lgkmcnt(0)
	v_add_f32_e32 v88, v88, v98
	v_fmamk_f32 v88, v88, 0x3a800000, v90
	v_mul_f32_e32 v98, 0x4b800000, v88
	v_cmp_gt_f32_e32 vcc, s25, v88
	s_nop 1
	v_cndmask_b32_e32 v88, v88, v98, vcc
	v_rsq_f32_e32 v88, v88
	s_nop 0
	v_mul_f32_e32 v98, 0x45800000, v88
	v_cndmask_b32_e32 v88, v88, v98, vcc
	v_pk_mul_f32 v[28:29], v[28:29], v[88:89] op_sel_hi:[1,0]
	v_pk_mul_f32 v[30:31], v[30:31], v[88:89] op_sel_hi:[1,0]
	v_pk_mul_f32 v[24:25], v[24:25], v[88:89] op_sel_hi:[1,0]
	v_pk_mul_f32 v[26:27], v[26:27], v[88:89] op_sel_hi:[1,0]
	v_pk_mul_f32 v[16:17], v[16:17], v[88:89] op_sel_hi:[1,0]
	v_pk_mul_f32 v[98:99], v[18:19], v[88:89] op_sel_hi:[1,0]
	s_nop 0
	v_pk_mul_f32 v[18:19], v[8:9], v[28:29]
	v_pk_mul_f32 v[28:29], v[10:11], v[30:31]
	s_nop 0
	v_pk_mul_f32 v[24:25], v[12:13], v[24:25]
	v_pk_mul_f32 v[26:27], v[14:15], v[26:27]
	v_pk_mul_f32 v[16:17], v[4:5], v[16:17]
	v_pk_fma_f32 v[18:19], v[80:81], v[18:19], v[36:37]
	v_pk_fma_f32 v[28:29], v[78:79], v[28:29], v[38:39]
	v_pk_fma_f32 v[24:25], v[76:77], v[24:25], v[32:33]
	v_pk_fma_f32 v[26:27], v[74:75], v[26:27], v[34:35]
	v_pk_mul_f32 v[20:21], v[20:21], v[88:89] op_sel_hi:[1,0]
	v_pk_mul_f32 v[22:23], v[22:23], v[88:89] op_sel_hi:[1,0]
	v_pk_fma_f32 v[30:31], v[82:83], v[16:17], v[40:41]
	v_cvt_pk_bf16_f32 v16, v18, v19
	v_cvt_pk_bf16_f32 v17, v28, v29
	v_cvt_pk_bf16_f32 v18, v24, v25
	v_cvt_pk_bf16_f32 v19, v26, v27
	v_pk_mul_f32 v[20:21], v[0:1], v[20:21]
	v_pk_mul_f32 v[22:23], v[2:3], v[22:23]
	global_store_dwordx4 v[70:71], v[16:19], off
	v_pk_fma_f32 v[20:21], v[72:73], v[20:21], v[44:45]
	v_pk_fma_f32 v[22:23], v[84:85], v[22:23], v[46:47]
	v_pk_mul_f32 v[16:17], v[6:7], v[98:99]
	v_cvt_pk_bf16_f32 v18, v30, v31
	v_pk_fma_f32 v[24:25], v[86:87], v[16:17], v[42:43]
	v_cvt_pk_bf16_f32 v16, v20, v21
	v_cvt_pk_bf16_f32 v17, v22, v23
	v_cvt_pk_bf16_f32 v19, v24, v25
	global_store_dwordx4 v[70:71], v[16:19], off offset:1024
	s_waitcnt vmcnt(3)
	v_mov_b64_e32 v[20:21], v[60:61]
	v_mov_b64_e32 v[24:25], v[48:49]
	v_mov_b64_e32 v[16:17], v[56:57]
	v_mov_b64_e32 v[28:29], v[52:53]
	v_lshl_add_u64 v[70:71], v[70:71], 0, s[14:15]
	v_mov_b64_e32 v[18:19], v[58:59]
	v_mov_b64_e32 v[22:23], v[62:63]
	v_mov_b64_e32 v[26:27], v[50:51]
	v_mov_b64_e32 v[30:31], v[54:55]
	v_mov_b32_e32 v88, v97
	s_andn2_b64 exec, exec, s[8:9]
	s_cbranch_execz .LBB0_238

.LBB0_236:
	s_or_b64 exec, exec, s[16:17]
	v_add_u32_e32 v122, s6, v97
	v_mov_b32_e32 v124, s19
	v_min_i32_e32 v122, 0x7fff, v122
	v_mov_b32_e32 v123, 0
	v_mov_b32_e32 v125, s18
	v_lshlrev_b64 v[122:123], 12, v[122:123]
	v_lshl_add_u64 v[122:123], v[124:125], 0, v[122:123]
	v_lshl_add_u64 v[122:123], v[64:65], 1, v[122:123]
	global_load_dword v126, v[122:123], off
	v_min_i32_e32 v88, 0x8000, v88
	v_ashrrev_i32_e32 v88, 13, v88
	v_cmp_ne_u32_e32 vcc, v88, v91
	s_and_saveexec_b64 s[16:17], vcc
	s_cbranch_execz .LBB0_233
	v_mul_hi_i32_i24_e32 v33, 0x3000, v88
	v_mul_i32_i24_e32 v32, 0x3000, v88
	v_lshl_add_u64 v[76:77], v[68:69], 0, v[32:33]
	v_add_co_u32_e32 v78, vcc, 0x1000, v76
	v_lshl_add_u64 v[32:33], v[76:77], 0, s[10:11]
	s_nop 0
	v_addc_co_u32_e32 v79, vcc, 0, v77, vcc
	global_load_dwordx4 v[72:75], v[78:79], off
	global_load_dwordx4 v[82:85], v[32:33], off offset:16
	v_lshl_add_u64 v[80:81], v[76:77], 0, s[12:13]
	global_load_dwordx4 v[98:101], v[78:79], off offset:2048
	global_load_dwordx4 v[102:105], v[80:81], off offset:16
	global_load_dwordx4 v[36:39], v[76:77], off
	global_load_dwordx4 v[32:35], v[76:77], off offset:16
	global_load_dwordx4 v[44:47], v[76:77], off offset:2048
	global_load_dwordx4 v[40:43], v[76:77], off offset:2064
	v_mov_b32_e32 v91, v88
	s_waitcnt vmcnt(0)
	v_pk_add_f32 v[86:87], v[104:105], 1.0 op_sel_hi:[1,0]
	v_pk_add_f32 v[80:81], v[72:73], 1.0 op_sel_hi:[1,0]
	v_pk_add_f32 v[78:79], v[74:75], 1.0 op_sel_hi:[1,0]
	v_pk_add_f32 v[76:77], v[82:83], 1.0 op_sel_hi:[1,0]
	v_pk_add_f32 v[74:75], v[84:85], 1.0 op_sel_hi:[1,0]
	v_pk_add_f32 v[72:73], v[98:99], 1.0 op_sel_hi:[1,0]
	v_pk_add_f32 v[84:85], v[100:101], 1.0 op_sel_hi:[1,0]
	v_pk_add_f32 v[82:83], v[102:103], 1.0 op_sel_hi:[1,0]
	s_branch .LBB0_233
